# v10 + attention K-tile loop back-edge rotation: exit test, skip test and next-tile flag/address setup moved in front of the loop barrier
# speedup vs baseline: 1.0087x; 1.0087x over previous
.LBB0_1523:
	s_add_i32 s69, s69, 64
	v_lshl_add_u64 v[174:175], v[174:175], 0, s[8:9]
	v_lshl_add_u64 v[176:177], v[176:177], 0, s[30:31]
	s_cmp_eq_u32 s67, s13
	v_lshl_add_u64 v[178:179], v[178:179], 0, s[36:37]
	s_cbranch_scc1 .Lat_exitbar
	v_mov_b32_e32 v188, v187
	s_mov_b32 s73, s13
	s_sub_i32 s13, s69, 63
	s_cmp_gt_i32 s13, s68
	s_cbranch_scc1 .Lat_skipbar
	s_bitcmp1_b32 s73, 0
	s_cselect_b32 s74, 0xac00, 0
	s_sub_i32 s13, s69, 31
	s_cmp_gt_i32 s13, s68
	s_cselect_b64 s[42:43], -1, 0
	s_cmp_le_i32 s13, s68
	s_cselect_b64 s[40:41], -1, 0
	s_mov_b64 s[14:15], -1
	s_and_b64 vcc, exec, s[42:43]
	v_add_u32_e32 v187, s74, v185
	s_waitcnt lgkmcnt(0)
	s_barrier
	s_setprio 1
	s_cbranch_vccnz .LBB0_1534
.Lat_qk:
	ds_read_b128 v[64:67], v187
	ds_read_b128 v[190:193], v187 offset:32
	s_waitcnt lgkmcnt(1)
	v_mfma_f32_32x32x16_bf16 v[80:95], v[64:67], v[96:99], 0
	ds_read_b128 v[64:67], v187 offset:12800
	ds_read_b128 v[194:197], v187 offset:12832
	s_waitcnt lgkmcnt(1)
	v_mfma_f32_32x32x16_bf16 v[64:79], v[64:67], v[96:99], 0
	v_mfma_f32_32x32x16_bf16 v[80:95], v[190:193], v[100:103], v[80:95]
	s_waitcnt lgkmcnt(0)
	v_mfma_f32_32x32x16_bf16 v[64:79], v[194:197], v[100:103], v[64:79]
	ds_read_b128 v[190:193], v187 offset:64
	ds_read_b128 v[194:197], v187 offset:96
	s_waitcnt lgkmcnt(1)
	v_mfma_f32_32x32x16_bf16 v[80:95], v[190:193], v[104:107], v[80:95]
	ds_read_b128 v[190:193], v187 offset:12864
	ds_read_b128 v[198:201], v187 offset:12896
	s_waitcnt lgkmcnt(1)
	v_mfma_f32_32x32x16_bf16 v[64:79], v[190:193], v[104:107], v[64:79]
	v_mfma_f32_32x32x16_bf16 v[80:95], v[194:197], v[108:111], v[80:95]
	ds_read_b128 v[190:193], v187 offset:128
	ds_read_b128 v[194:197], v187 offset:160
	s_waitcnt lgkmcnt(2)
	v_mfma_f32_32x32x16_bf16 v[64:79], v[198:201], v[108:111], v[64:79]
	s_waitcnt lgkmcnt(1)
	v_mfma_f32_32x32x16_bf16 v[80:95], v[190:193], v[112:115], v[80:95]
	ds_read_b128 v[190:193], v187 offset:12928
	ds_read_b128 v[198:201], v187 offset:12960
	s_waitcnt lgkmcnt(1)
	v_mfma_f32_32x32x16_bf16 v[64:79], v[190:193], v[112:115], v[64:79]
	v_mfma_f32_32x32x16_bf16 v[80:95], v[194:197], v[116:119], v[80:95]
	ds_read_b128 v[190:193], v187 offset:192
	ds_read_b128 v[194:197], v187 offset:224
	s_waitcnt lgkmcnt(2)
	v_mfma_f32_32x32x16_bf16 v[64:79], v[198:201], v[116:119], v[64:79]
	s_waitcnt lgkmcnt(1)
	v_mfma_f32_32x32x16_bf16 v[80:95], v[190:193], v[120:123], v[80:95]
	ds_read_b128 v[190:193], v187 offset:12992
	ds_read_b128 v[198:201], v187 offset:13024
	s_waitcnt lgkmcnt(1)
	v_mfma_f32_32x32x16_bf16 v[64:79], v[190:193], v[120:123], v[64:79]
	v_mfma_f32_32x32x16_bf16 v[80:95], v[194:197], v[124:127], v[80:95]
	ds_read_b128 v[190:193], v187 offset:256
	ds_read_b128 v[194:197], v187 offset:288
	s_waitcnt lgkmcnt(2)
	v_mfma_f32_32x32x16_bf16 v[64:79], v[198:201], v[124:127], v[64:79]
	s_waitcnt lgkmcnt(1)
	v_mfma_f32_32x32x16_bf16 v[80:95], v[190:193], v[128:131], v[80:95]
	ds_read_b128 v[190:193], v187 offset:13056
	ds_read_b128 v[198:201], v187 offset:13088
	s_waitcnt lgkmcnt(1)
	v_mfma_f32_32x32x16_bf16 v[64:79], v[190:193], v[128:131], v[64:79]
	v_mfma_f32_32x32x16_bf16 v[80:95], v[194:197], v[132:135], v[80:95]
	ds_read_b128 v[190:193], v187 offset:320
	ds_read_b128 v[194:197], v187 offset:352
	s_waitcnt lgkmcnt(2)
	v_mfma_f32_32x32x16_bf16 v[64:79], v[198:201], v[132:135], v[64:79]
	s_waitcnt lgkmcnt(1)
	v_mfma_f32_32x32x16_bf16 v[80:95], v[190:193], v[136:139], v[80:95]
	ds_read_b128 v[190:193], v187 offset:13120
	ds_read_b128 v[198:201], v187 offset:13152
	s_waitcnt lgkmcnt(1)
	v_mfma_f32_32x32x16_bf16 v[64:79], v[190:193], v[136:139], v[64:79]
	v_mfma_f32_32x32x16_bf16 v[80:95], v[194:197], v[140:143], v[80:95]
	s_waitcnt lgkmcnt(0)
	v_mfma_f32_32x32x16_bf16 v[64:79], v[198:201], v[140:143], v[64:79]
	s_cbranch_execz .LBB0_1535

.Lat_exitbar:
	s_waitcnt lgkmcnt(0)
	s_barrier
	s_branch .LBB0_1536
.Lat_skipbar:
	s_waitcnt lgkmcnt(0)
	s_barrier
	s_setprio 1
	s_branch .LBB0_1519
.LBB0_1525:
	s_bitcmp1_b32 s73, 0
	s_cselect_b32 s74, 0xac00, 0
	s_sub_i32 s13, s69, 31
	s_cmp_gt_i32 s13, s68
	s_cselect_b64 s[42:43], -1, 0
	s_cmp_le_i32 s13, s68
	s_cselect_b64 s[40:41], -1, 0
	s_mov_b64 s[14:15], -1
	s_and_b64 vcc, exec, s[42:43]
	v_add_u32_e32 v187, s74, v185
	s_cbranch_vccnz .LBB0_1534
	s_branch .Lat_qk
